# attention tile loops: s_setprio 1 around MFMA bursts (QK and PV), 0 elsewhere
# baseline (speedup 1.0000x reference)
.LBB0_906:
	s_waitcnt lgkmcnt(0)
	s_barrier
	ds_read_b128 v[64:67], v181
	ds_read_b128 v[194:197], v181 offset:32
	s_waitcnt lgkmcnt(1)
	s_setprio 1
	v_mfma_f32_32x32x16_bf16 v[80:95], v[64:67], v[96:99], 0
	s_setprio 0
	ds_read_b128 v[64:67], v181 offset:8704
	ds_read_b128 v[198:201], v181 offset:8736
	s_cmp_lt_i32 s48, s42
	s_cselect_b64 s[18:19], -1, 0
	s_and_b64 s[18:19], s[14:15], s[18:19]
	s_andn2_b64 vcc, exec, s[18:19]
	s_waitcnt lgkmcnt(1)
	s_setprio 1
	v_mfma_f32_32x32x16_bf16 v[64:79], v[64:67], v[96:99], 0
	v_mfma_f32_32x32x16_bf16 v[80:95], v[194:197], v[100:103], v[80:95]
	s_waitcnt lgkmcnt(0)
	v_mfma_f32_32x32x16_bf16 v[64:79], v[198:201], v[100:103], v[64:79]
	ds_read_b128 v[194:197], v181 offset:64
	ds_read_b128 v[198:201], v181 offset:96
	s_waitcnt lgkmcnt(1)
	v_mfma_f32_32x32x16_bf16 v[80:95], v[194:197], v[104:107], v[80:95]
	ds_read_b128 v[194:197], v181 offset:8768
	ds_read_b128 v[202:205], v181 offset:8800
	s_waitcnt lgkmcnt(1)
	v_mfma_f32_32x32x16_bf16 v[64:79], v[194:197], v[104:107], v[64:79]
	v_mfma_f32_32x32x16_bf16 v[80:95], v[198:201], v[108:111], v[80:95]
	ds_read_b128 v[194:197], v181 offset:128
	ds_read_b128 v[198:201], v181 offset:160
	s_waitcnt lgkmcnt(2)
	v_mfma_f32_32x32x16_bf16 v[64:79], v[202:205], v[108:111], v[64:79]
	s_waitcnt lgkmcnt(1)
	v_mfma_f32_32x32x16_bf16 v[80:95], v[194:197], v[112:115], v[80:95]
	ds_read_b128 v[194:197], v181 offset:8832
	ds_read_b128 v[202:205], v181 offset:8864
	s_waitcnt lgkmcnt(1)
	v_mfma_f32_32x32x16_bf16 v[64:79], v[194:197], v[112:115], v[64:79]
	v_mfma_f32_32x32x16_bf16 v[80:95], v[198:201], v[116:119], v[80:95]
	ds_read_b128 v[194:197], v181 offset:192
	ds_read_b128 v[198:201], v181 offset:224
	s_waitcnt lgkmcnt(2)
	v_mfma_f32_32x32x16_bf16 v[64:79], v[202:205], v[116:119], v[64:79]
	s_waitcnt lgkmcnt(1)
	v_mfma_f32_32x32x16_bf16 v[80:95], v[194:197], v[120:123], v[80:95]
	ds_read_b128 v[194:197], v181 offset:8896
	ds_read_b128 v[202:205], v181 offset:8928
	s_waitcnt lgkmcnt(1)
	v_mfma_f32_32x32x16_bf16 v[64:79], v[194:197], v[120:123], v[64:79]
	v_mfma_f32_32x32x16_bf16 v[80:95], v[198:201], v[124:127], v[80:95]
	s_waitcnt lgkmcnt(0)
	v_mfma_f32_32x32x16_bf16 v[64:79], v[202:205], v[124:127], v[64:79]
	s_setprio 0
	s_cbranch_vccnz .LBB0_908
	v_add_u32_e32 v159, 27, v191
	v_sub_u32_e32 v194, 0xffffffe5, v191
	v_add_u32_e32 v196, s43, v190
	v_max_i32_e32 v194, v159, v194
	v_add_u32_e32 v195, -5, v191
	v_add_u32_e32 v197, 32, v196
	v_cmp_gt_i32_e32 vcc, 32, v159
	s_nop 1
	v_cndmask_b32_e32 v159, v195, v197, vcc
	v_cmp_gt_u32_e32 vcc, s31, v194
	v_sub_u32_e32 v194, 0xffffffe6, v191
	v_add_u32_e32 v195, -6, v191
	v_cndmask_b32_e32 v80, v185, v80, vcc
	v_cmp_gt_i32_e32 vcc, s31, v159
	v_add_u32_e32 v159, 26, v191
	v_max_i32_e32 v194, v159, v194
	v_cndmask_b32_e32 v64, v185, v64, vcc
	v_add_u32_e32 v197, 33, v196
	v_cmp_gt_i32_e32 vcc, 32, v159
	s_nop 1
	v_cndmask_b32_e32 v159, v195, v197, vcc
	v_cmp_gt_u32_e32 vcc, s31, v194
	v_sub_u32_e32 v194, 0xffffffe7, v191
	v_add_u32_e32 v195, -7, v191
	v_cndmask_b32_e32 v81, v185, v81, vcc
	v_cmp_gt_i32_e32 vcc, s31, v159
	v_add_u32_e32 v159, 25, v191
	v_max_i32_e32 v194, v159, v194
	v_cndmask_b32_e32 v65, v185, v65, vcc
	v_add_u32_e32 v197, 34, v196
	v_cmp_gt_i32_e32 vcc, 32, v159
	s_nop 1
	v_cndmask_b32_e32 v159, v195, v197, vcc
	v_cmp_gt_u32_e32 vcc, s31, v194
	v_sub_u32_e32 v194, 0xffffffe8, v191
	v_add_u32_e32 v195, -8, v191
	v_cndmask_b32_e32 v82, v185, v82, vcc
	v_cmp_gt_i32_e32 vcc, s31, v159
	v_add_u32_e32 v159, 24, v191
	v_max_i32_e32 v194, v159, v194
	v_cndmask_b32_e32 v66, v185, v66, vcc
	v_add_u32_e32 v197, 35, v196
	v_cmp_gt_i32_e32 vcc, 32, v159
	s_nop 1
	v_cndmask_b32_e32 v159, v195, v197, vcc
	v_cmp_gt_u32_e32 vcc, s31, v194
	v_sub_u32_e32 v194, 0xffffffed, v191
	v_add_u32_e32 v195, -13, v191
	v_cndmask_b32_e32 v83, v185, v83, vcc
	v_cmp_gt_i32_e32 vcc, s31, v159
	v_add_u32_e32 v159, 19, v191
	v_max_i32_e32 v194, v159, v194
	v_cndmask_b32_e32 v67, v185, v67, vcc
	v_add_u32_e32 v197, 40, v196
	v_cmp_gt_i32_e32 vcc, 32, v159
	s_nop 1
	v_cndmask_b32_e32 v159, v195, v197, vcc
	v_cmp_gt_u32_e32 vcc, s31, v194
	v_sub_u32_e32 v194, 0xffffffee, v191
	v_add_u32_e32 v195, -14, v191
	v_cndmask_b32_e32 v84, v185, v84, vcc
	v_cmp_gt_i32_e32 vcc, s31, v159
	v_add_u32_e32 v159, 18, v191
	v_max_i32_e32 v194, v159, v194
	v_cndmask_b32_e32 v68, v185, v68, vcc
	v_add_u32_e32 v197, 41, v196
	v_cmp_gt_i32_e32 vcc, 32, v159
	s_nop 1
	v_cndmask_b32_e32 v159, v195, v197, vcc
	v_cmp_gt_u32_e32 vcc, s31, v194
	v_sub_u32_e32 v194, 0xffffffef, v191
	v_add_u32_e32 v195, -15, v191
	v_cndmask_b32_e32 v85, v185, v85, vcc
	v_cmp_gt_i32_e32 vcc, s31, v159
	v_add_u32_e32 v159, 17, v191
	v_max_i32_e32 v194, v159, v194
	v_cndmask_b32_e32 v69, v185, v69, vcc
	v_add_u32_e32 v197, 42, v196
	v_cmp_gt_i32_e32 vcc, 32, v159
	s_nop 1
	v_cndmask_b32_e32 v159, v195, v197, vcc
	v_cmp_gt_u32_e32 vcc, s31, v194
	v_sub_u32_e32 v194, -16, v191
	v_add_u32_e32 v195, -16, v191
	v_cndmask_b32_e32 v86, v185, v86, vcc
	v_cmp_gt_i32_e32 vcc, s31, v159
	v_add_u32_e32 v159, 16, v191
	v_max_i32_e32 v194, v159, v194
	v_cndmask_b32_e32 v70, v185, v70, vcc
	v_add_u32_e32 v197, 43, v196
	v_cmp_gt_i32_e32 vcc, 32, v159
	s_nop 1
	v_cndmask_b32_e32 v159, v195, v197, vcc
	v_cmp_gt_u32_e32 vcc, s31, v194
	v_sub_u32_e32 v194, -11, v191
	v_subrev_u32_e32 v195, 21, v191
	v_cndmask_b32_e32 v87, v185, v87, vcc
	v_cmp_gt_i32_e32 vcc, s31, v159
	v_add_u32_e32 v159, 11, v191
	v_max_i32_e32 v194, v159, v194
	v_cndmask_b32_e32 v71, v185, v71, vcc
	v_add_u32_e32 v197, 48, v196
	v_cmp_gt_i32_e32 vcc, 32, v159
	s_nop 1
	v_cndmask_b32_e32 v159, v195, v197, vcc
	v_cmp_gt_u32_e32 vcc, s31, v194
	v_sub_u32_e32 v194, -10, v191
	v_subrev_u32_e32 v195, 22, v191
	v_cndmask_b32_e32 v88, v185, v88, vcc
	v_cmp_gt_i32_e32 vcc, s31, v159
	v_add_u32_e32 v159, 10, v191
	v_max_i32_e32 v194, v159, v194
	v_cndmask_b32_e32 v72, v185, v72, vcc
	v_add_u32_e32 v197, 49, v196
	v_cmp_gt_i32_e32 vcc, 32, v159
	s_nop 1
	v_cndmask_b32_e32 v159, v195, v197, vcc
	v_cmp_gt_u32_e32 vcc, s31, v194
	v_sub_u32_e32 v194, -9, v191
	v_subrev_u32_e32 v195, 23, v191
	v_cndmask_b32_e32 v89, v185, v89, vcc
	v_cmp_gt_i32_e32 vcc, s31, v159
	v_add_u32_e32 v159, 9, v191
	v_max_i32_e32 v194, v159, v194
	v_cndmask_b32_e32 v73, v185, v73, vcc
	v_add_u32_e32 v197, 50, v196
	v_cmp_gt_i32_e32 vcc, 32, v159
	s_nop 1
	v_cndmask_b32_e32 v159, v195, v197, vcc
	v_cmp_gt_u32_e32 vcc, s31, v194
	v_sub_u32_e32 v194, -8, v191
	v_subrev_u32_e32 v195, 24, v191
	v_cndmask_b32_e32 v90, v185, v90, vcc
	v_cmp_gt_i32_e32 vcc, s31, v159
	v_add_u32_e32 v159, 8, v191
	v_max_i32_e32 v194, v159, v194
	v_cndmask_b32_e32 v74, v185, v74, vcc
	v_add_u32_e32 v197, 51, v196
	v_cmp_gt_i32_e32 vcc, 32, v159
	s_nop 1
	v_cndmask_b32_e32 v159, v195, v197, vcc
	v_cmp_gt_u32_e32 vcc, s31, v194
	v_sub_u32_e32 v194, -3, v191
	v_subrev_u32_e32 v195, 29, v191
	v_cndmask_b32_e32 v91, v185, v91, vcc
	v_cmp_gt_i32_e32 vcc, s31, v159
	v_add_u32_e32 v159, 3, v191
	v_max_i32_e32 v194, v159, v194
	v_cndmask_b32_e32 v75, v185, v75, vcc
	v_add_u32_e32 v197, 56, v196
	v_cmp_gt_i32_e32 vcc, 32, v159
	s_nop 1
	v_cndmask_b32_e32 v159, v195, v197, vcc
	v_cmp_gt_u32_e32 vcc, s31, v194
	v_sub_u32_e32 v194, -2, v191
	v_subrev_u32_e32 v195, 30, v191
	v_cndmask_b32_e32 v92, v185, v92, vcc
	v_cmp_gt_i32_e32 vcc, s31, v159
	v_add_u32_e32 v159, 2, v191
	v_max_i32_e32 v194, v159, v194
	v_cndmask_b32_e32 v76, v185, v76, vcc
	v_add_u32_e32 v197, 57, v196
	v_cmp_gt_i32_e32 vcc, 32, v159
	s_nop 1
	v_cndmask_b32_e32 v159, v195, v197, vcc
	v_cmp_gt_u32_e32 vcc, s31, v194
	v_not_b32_e32 v194, v191
	v_subrev_u32_e32 v195, 31, v191
	v_cndmask_b32_e32 v93, v185, v93, vcc
	v_cmp_gt_i32_e32 vcc, s31, v159
	v_add_u32_e32 v159, 1, v191
	v_max_i32_e32 v194, v159, v194
	v_cndmask_b32_e32 v77, v185, v77, vcc
	v_add_u32_e32 v197, 58, v196
	v_cmp_gt_i32_e32 vcc, 32, v159
	s_nop 1
	v_cndmask_b32_e32 v159, v195, v197, vcc
	v_cmp_gt_u32_e32 vcc, s31, v194
	v_subrev_u32_e32 v194, 32, v191
	v_add_u32_e32 v195, 59, v196
	v_cndmask_b32_e32 v94, v185, v94, vcc
	v_cmp_gt_i32_e32 vcc, s31, v159
	v_sub_u32_e32 v159, 0, v191
	v_max_i32_e32 v159, v191, v159
	v_cndmask_b32_e32 v78, v185, v78, vcc
	v_cmp_gt_i32_e32 vcc, 32, v191
	s_nop 1
	v_cndmask_b32_e32 v194, v194, v195, vcc
	v_cmp_gt_u32_e32 vcc, s31, v159
	s_nop 1
	v_cndmask_b32_e32 v95, v185, v95, vcc
	v_cmp_gt_i32_e32 vcc, s31, v194
	s_nop 1
	v_cndmask_b32_e32 v79, v185, v79, vcc

.LBB0_912:
	v_sub_f32_e32 v64, v64, v159
	v_exp_f32_e32 v195, v64
	v_sub_f32_e32 v64, v81, v159
	v_exp_f32_e32 v196, v64
	v_sub_f32_e32 v64, v65, v159
	v_exp_f32_e32 v197, v64
	v_sub_f32_e32 v64, v82, v159
	v_exp_f32_e32 v198, v64
	v_sub_f32_e32 v64, v66, v159
	v_exp_f32_e32 v199, v64
	v_sub_f32_e32 v64, v83, v159
	v_exp_f32_e32 v200, v64
	v_sub_f32_e32 v64, v67, v159
	v_exp_f32_e32 v201, v64
	v_sub_f32_e32 v64, v84, v159
	v_exp_f32_e32 v84, v64
	v_sub_f32_e32 v64, v68, v159
	v_exp_f32_e32 v202, v64
	v_sub_f32_e32 v64, v85, v159
	v_exp_f32_e32 v85, v64
	v_sub_f32_e32 v64, v69, v159
	v_exp_f32_e32 v203, v64
	v_sub_f32_e32 v64, v86, v159
	v_exp_f32_e32 v86, v64
	v_sub_f32_e32 v64, v70, v159
	v_exp_f32_e32 v204, v64
	v_sub_f32_e32 v64, v87, v159
	v_exp_f32_e32 v87, v64
	v_sub_f32_e32 v64, v71, v159
	v_exp_f32_e32 v205, v64
	v_sub_f32_e32 v64, v88, v159
	v_exp_f32_e32 v88, v64
	v_sub_f32_e32 v64, v72, v159
	v_exp_f32_e32 v206, v64
	v_sub_f32_e32 v64, v89, v159
	v_exp_f32_e32 v89, v64
	v_sub_f32_e32 v64, v73, v159
	v_exp_f32_e32 v207, v64
	v_sub_f32_e32 v64, v90, v159
	v_exp_f32_e32 v90, v64
	v_sub_f32_e32 v64, v74, v159
	v_exp_f32_e32 v208, v64
	v_sub_f32_e32 v64, v91, v159
	v_exp_f32_e32 v91, v64
	v_sub_f32_e32 v64, v75, v159
	v_sub_f32_e32 v80, v80, v159
	v_exp_f32_e32 v209, v64
	v_sub_f32_e32 v64, v92, v159
	v_exp_f32_e32 v194, v80
	v_exp_f32_e32 v92, v64
	v_sub_f32_e32 v64, v76, v159
	v_exp_f32_e32 v212, v64
	v_sub_f32_e32 v64, v93, v159
	v_exp_f32_e32 v93, v64
	v_sub_f32_e32 v64, v77, v159
	v_exp_f32_e32 v213, v64
	v_sub_f32_e32 v64, v94, v159
	v_add_u32_e32 v214, 0x4000, v182
	v_exp_f32_e32 v94, v64
	v_cvt_pk_bf16_f32 v64, v194, v196
	v_cvt_pk_bf16_f32 v65, v198, v200
	v_cvt_pk_bf16_f32 v66, v84, v85
	v_cvt_pk_bf16_f32 v67, v86, v87
	ds_read2_b64 v[68:71], v214 offset0:128 offset1:130
	v_sub_f32_e32 v72, v95, v159
	v_exp_f32_e32 v95, v72
	s_waitcnt lgkmcnt(0)
	s_setprio 1
	v_mfma_f32_32x32x16_bf16 v[32:47], v[64:67], v[68:71], v[32:47]
	s_setprio 0
	v_cvt_pk_bf16_f32 v72, v88, v89
	v_cvt_pk_bf16_f32 v73, v90, v91
	v_cvt_pk_bf16_f32 v74, v92, v93
	v_cvt_pk_bf16_f32 v75, v94, v95
	ds_read2_b64 v[68:71], v214 offset0:132 offset1:134
	v_cvt_pk_bf16_f32 v80, v195, v197
	v_cvt_pk_bf16_f32 v81, v199, v201
	s_waitcnt lgkmcnt(0)
	s_setprio 1
	v_mfma_f32_32x32x16_bf16 v[32:47], v[72:75], v[68:71], v[32:47]
	s_setprio 0
	v_cvt_pk_bf16_f32 v82, v202, v203
	v_cvt_pk_bf16_f32 v83, v204, v205
	ds_read2_b64 v[68:71], v214 offset0:136 offset1:138
	v_sub_f32_e32 v76, v78, v159
	v_exp_f32_e32 v215, v76
	v_sub_f32_e32 v76, v79, v159
	v_exp_f32_e32 v216, v76
	s_waitcnt lgkmcnt(0)
	s_setprio 1
	v_mfma_f32_32x32x16_bf16 v[32:47], v[80:83], v[68:71], v[32:47]
	s_setprio 0
	v_cvt_pk_bf16_f32 v76, v206, v207
	v_cvt_pk_bf16_f32 v77, v208, v209
	v_cvt_pk_bf16_f32 v78, v212, v213
	v_cvt_pk_bf16_f32 v79, v215, v216
	ds_read2_b64 v[68:71], v214 offset0:140 offset1:142
	v_add_u32_e32 v214, 0x5000, v182
	v_add_f32_e32 v194, v194, v195
	s_waitcnt lgkmcnt(0)
	s_setprio 1
	v_mfma_f32_32x32x16_bf16 v[32:47], v[76:79], v[68:71], v[32:47]
	s_setprio 0
	ds_read2_b64 v[68:71], v214 offset0:192 offset1:194
	v_add_f32_e32 v194, 0, v194
	v_add_f32_e32 v195, v196, v197
	v_add_f32_e32 v194, v195, v194
	v_add_f32_e32 v195, v200, v201
	v_add_f32_e32 v84, v84, v202
	v_add_f32_e32 v85, v85, v203
	s_waitcnt lgkmcnt(0)
	s_setprio 1
	v_mfma_f32_32x32x16_bf16 v[48:63], v[64:67], v[68:71], v[48:63]
	s_setprio 0
	ds_read2_b64 v[68:71], v214 offset0:196 offset1:198
	s_add_i32 s43, s43, 64
	s_cmp_eq_u32 s41, s47
	v_subrev_u32_e32 v191, 64, v191
	s_waitcnt lgkmcnt(0)
	s_setprio 1
	v_mfma_f32_32x32x16_bf16 v[48:63], v[72:75], v[68:71], v[48:63]
	ds_read2_b64 v[68:71], v214 offset0:200 offset1:202
	s_waitcnt lgkmcnt(0)
	v_mfma_f32_32x32x16_bf16 v[48:63], v[80:83], v[68:71], v[48:63]
	ds_read2_b64 v[68:71], v214 offset0:204 offset1:206
	v_add_u32_e32 v214, 0x6800, v182
	s_waitcnt lgkmcnt(0)
	v_mfma_f32_32x32x16_bf16 v[48:63], v[76:79], v[68:71], v[48:63]
	ds_read2_b64 v[68:71], v214 offset1:2
	s_waitcnt lgkmcnt(0)
	v_mfma_f32_32x32x16_bf16 v[16:31], v[64:67], v[68:71], v[16:31]
	ds_read2_b64 v[68:71], v214 offset0:4 offset1:6
	s_waitcnt lgkmcnt(0)
	v_mfma_f32_32x32x16_bf16 v[16:31], v[72:75], v[68:71], v[16:31]
	ds_read2_b64 v[68:71], v214 offset0:8 offset1:10
	s_waitcnt lgkmcnt(0)
	v_mfma_f32_32x32x16_bf16 v[16:31], v[80:83], v[68:71], v[16:31]
	s_setprio 0
	v_add_f32_e32 v68, v198, v199
	v_add_f32_e32 v194, v68, v194
	ds_read2_b64 v[68:71], v214 offset0:12 offset1:14
	v_add_f32_e32 v194, v195, v194
	v_add_f32_e32 v84, v84, v194
	v_add_u32_e32 v194, 0x7800, v182
	v_add_f32_e32 v84, v85, v84
	s_waitcnt lgkmcnt(0)
	s_setprio 1
	v_mfma_f32_32x32x16_bf16 v[16:31], v[76:79], v[68:71], v[16:31]
	s_setprio 0
	ds_read2_b64 v[68:71], v194 offset0:64 offset1:66
	v_add_f32_e32 v85, v86, v204
	v_add_f32_e32 v84, v85, v84
	v_add_f32_e32 v85, v87, v205
	s_waitcnt lgkmcnt(0)
	s_setprio 1
	v_mfma_f32_32x32x16_bf16 v[0:15], v[64:67], v[68:71], v[0:15]
	s_setprio 0
	ds_read2_b64 v[64:67], v194 offset0:68 offset1:70
	v_add_f32_e32 v68, v85, v84
	v_add_f32_e32 v69, v88, v206
	v_add_f32_e32 v68, v69, v68
	v_add_f32_e32 v69, v89, v207
	v_add_f32_e32 v68, v69, v68
	v_add_f32_e32 v69, v90, v208
	s_waitcnt lgkmcnt(0)
	s_setprio 1
	v_mfma_f32_32x32x16_bf16 v[0:15], v[72:75], v[64:67], v[0:15]
	s_setprio 0
	ds_read2_b64 v[64:67], v194 offset0:72 offset1:74
	v_add_f32_e32 v68, v69, v68
	v_add_f32_e32 v69, v91, v209
	v_add_f32_e32 v68, v69, v68
	v_add_f32_e32 v69, v92, v212
	v_add_f32_e32 v68, v69, v68
	v_add_f32_e32 v69, v93, v213
	s_waitcnt lgkmcnt(0)
	s_setprio 1
	v_mfma_f32_32x32x16_bf16 v[0:15], v[80:83], v[64:67], v[0:15]
	s_setprio 0
	v_add_f32_e32 v64, v69, v68
	ds_read2_b64 v[66:69], v194 offset0:76 offset1:78
	v_add_f32_e32 v65, v94, v215
	v_add_f32_e32 v64, v65, v64
	v_add_f32_e32 v65, v95, v216
	v_add_f32_e32 v64, v65, v64
	v_fmac_f32_e32 v64, v192, v193
	s_waitcnt lgkmcnt(0)
	s_setprio 1
	v_mfma_f32_32x32x16_bf16 v[0:15], v[76:79], v[66:69], v[0:15]
	s_setprio 0
	s_cbranch_scc1 .LBB0_914
	v_mov_b32_e32 v192, v64
	v_mov_b32_e32 v193, v159
	s_mov_b32 s48, s47
	s_branch .LBB0_897

.LBB0_945:
	s_waitcnt lgkmcnt(0)
	s_barrier
	ds_read_b128 v[64:67], v179
	ds_read_b128 v[192:195], v179 offset:32
	s_waitcnt lgkmcnt(1)
	s_setprio 1
	v_mfma_f32_32x32x16_bf16 v[80:95], v[64:67], v[96:99], 0
	s_setprio 0
	ds_read_b128 v[64:67], v179 offset:8704
	ds_read_b128 v[196:199], v179 offset:8736
	s_cmp_lt_i32 s48, s42
	s_cselect_b64 s[18:19], -1, 0
	s_and_b64 s[18:19], s[14:15], s[18:19]
	s_andn2_b64 vcc, exec, s[18:19]
	s_waitcnt lgkmcnt(1)
	s_setprio 1
	v_mfma_f32_32x32x16_bf16 v[64:79], v[64:67], v[96:99], 0
	v_mfma_f32_32x32x16_bf16 v[80:95], v[192:195], v[100:103], v[80:95]
	s_waitcnt lgkmcnt(0)
	v_mfma_f32_32x32x16_bf16 v[64:79], v[196:199], v[100:103], v[64:79]
	ds_read_b128 v[192:195], v179 offset:64
	ds_read_b128 v[196:199], v179 offset:96
	s_waitcnt lgkmcnt(1)
	v_mfma_f32_32x32x16_bf16 v[80:95], v[192:195], v[104:107], v[80:95]
	ds_read_b128 v[192:195], v179 offset:8768
	ds_read_b128 v[200:203], v179 offset:8800
	s_waitcnt lgkmcnt(1)
	v_mfma_f32_32x32x16_bf16 v[64:79], v[192:195], v[104:107], v[64:79]
	v_mfma_f32_32x32x16_bf16 v[80:95], v[196:199], v[108:111], v[80:95]
	ds_read_b128 v[192:195], v179 offset:128
	ds_read_b128 v[196:199], v179 offset:160
	s_waitcnt lgkmcnt(2)
	v_mfma_f32_32x32x16_bf16 v[64:79], v[200:203], v[108:111], v[64:79]
	s_waitcnt lgkmcnt(1)
	v_mfma_f32_32x32x16_bf16 v[80:95], v[192:195], v[112:115], v[80:95]
	ds_read_b128 v[192:195], v179 offset:8832
	ds_read_b128 v[200:203], v179 offset:8864
	s_waitcnt lgkmcnt(1)
	v_mfma_f32_32x32x16_bf16 v[64:79], v[192:195], v[112:115], v[64:79]
	v_mfma_f32_32x32x16_bf16 v[80:95], v[196:199], v[116:119], v[80:95]
	ds_read_b128 v[192:195], v179 offset:192
	ds_read_b128 v[196:199], v179 offset:224
	s_waitcnt lgkmcnt(2)
	v_mfma_f32_32x32x16_bf16 v[64:79], v[200:203], v[116:119], v[64:79]
	s_waitcnt lgkmcnt(1)
	v_mfma_f32_32x32x16_bf16 v[80:95], v[192:195], v[120:123], v[80:95]
	ds_read_b128 v[192:195], v179 offset:8896
	ds_read_b128 v[200:203], v179 offset:8928
	s_waitcnt lgkmcnt(1)
	v_mfma_f32_32x32x16_bf16 v[64:79], v[192:195], v[120:123], v[64:79]
	v_mfma_f32_32x32x16_bf16 v[80:95], v[196:199], v[124:127], v[80:95]
	s_waitcnt lgkmcnt(0)
	v_mfma_f32_32x32x16_bf16 v[64:79], v[200:203], v[124:127], v[64:79]
	s_setprio 0
	s_cbranch_vccnz .LBB0_947
	v_add_u32_e32 v157, 27, v189
	v_sub_u32_e32 v192, 0xffffffe5, v189
	v_add_u32_e32 v194, s43, v188
	v_max_i32_e32 v192, v157, v192
	v_add_u32_e32 v193, -5, v189
	v_add_u32_e32 v195, 32, v194
	v_cmp_gt_i32_e32 vcc, 32, v157
	s_nop 1
	v_cndmask_b32_e32 v157, v193, v195, vcc
	v_cmp_gt_u32_e32 vcc, s33, v192
	v_sub_u32_e32 v192, 0xffffffe6, v189
	v_add_u32_e32 v193, -6, v189
	v_cndmask_b32_e32 v80, v183, v80, vcc
	v_cmp_gt_i32_e32 vcc, s33, v157
	v_add_u32_e32 v157, 26, v189
	v_max_i32_e32 v192, v157, v192
	v_cndmask_b32_e32 v64, v183, v64, vcc
	v_add_u32_e32 v195, 33, v194
	v_cmp_gt_i32_e32 vcc, 32, v157
	s_nop 1
	v_cndmask_b32_e32 v157, v193, v195, vcc
	v_cmp_gt_u32_e32 vcc, s33, v192
	v_sub_u32_e32 v192, 0xffffffe7, v189
	v_add_u32_e32 v193, -7, v189
	v_cndmask_b32_e32 v81, v183, v81, vcc
	v_cmp_gt_i32_e32 vcc, s33, v157
	v_add_u32_e32 v157, 25, v189
	v_max_i32_e32 v192, v157, v192
	v_cndmask_b32_e32 v65, v183, v65, vcc
	v_add_u32_e32 v195, 34, v194
	v_cmp_gt_i32_e32 vcc, 32, v157
	s_nop 1
	v_cndmask_b32_e32 v157, v193, v195, vcc
	v_cmp_gt_u32_e32 vcc, s33, v192
	v_sub_u32_e32 v192, 0xffffffe8, v189
	v_add_u32_e32 v193, -8, v189
	v_cndmask_b32_e32 v82, v183, v82, vcc
	v_cmp_gt_i32_e32 vcc, s33, v157
	v_add_u32_e32 v157, 24, v189
	v_max_i32_e32 v192, v157, v192
	v_cndmask_b32_e32 v66, v183, v66, vcc
	v_add_u32_e32 v195, 35, v194
	v_cmp_gt_i32_e32 vcc, 32, v157
	s_nop 1
	v_cndmask_b32_e32 v157, v193, v195, vcc
	v_cmp_gt_u32_e32 vcc, s33, v192
	v_sub_u32_e32 v192, 0xffffffed, v189
	v_add_u32_e32 v193, -13, v189
	v_cndmask_b32_e32 v83, v183, v83, vcc
	v_cmp_gt_i32_e32 vcc, s33, v157
	v_add_u32_e32 v157, 19, v189
	v_max_i32_e32 v192, v157, v192
	v_cndmask_b32_e32 v67, v183, v67, vcc
	v_add_u32_e32 v195, 40, v194
	v_cmp_gt_i32_e32 vcc, 32, v157
	s_nop 1
	v_cndmask_b32_e32 v157, v193, v195, vcc
	v_cmp_gt_u32_e32 vcc, s33, v192
	v_sub_u32_e32 v192, 0xffffffee, v189
	v_add_u32_e32 v193, -14, v189
	v_cndmask_b32_e32 v84, v183, v84, vcc
	v_cmp_gt_i32_e32 vcc, s33, v157
	v_add_u32_e32 v157, 18, v189
	v_max_i32_e32 v192, v157, v192
	v_cndmask_b32_e32 v68, v183, v68, vcc
	v_add_u32_e32 v195, 41, v194
	v_cmp_gt_i32_e32 vcc, 32, v157
	s_nop 1
	v_cndmask_b32_e32 v157, v193, v195, vcc
	v_cmp_gt_u32_e32 vcc, s33, v192
	v_sub_u32_e32 v192, 0xffffffef, v189
	v_add_u32_e32 v193, -15, v189
	v_cndmask_b32_e32 v85, v183, v85, vcc
	v_cmp_gt_i32_e32 vcc, s33, v157
	v_add_u32_e32 v157, 17, v189
	v_max_i32_e32 v192, v157, v192
	v_cndmask_b32_e32 v69, v183, v69, vcc
	v_add_u32_e32 v195, 42, v194
	v_cmp_gt_i32_e32 vcc, 32, v157
	s_nop 1
	v_cndmask_b32_e32 v157, v193, v195, vcc
	v_cmp_gt_u32_e32 vcc, s33, v192
	v_sub_u32_e32 v192, -16, v189
	v_add_u32_e32 v193, -16, v189
	v_cndmask_b32_e32 v86, v183, v86, vcc
	v_cmp_gt_i32_e32 vcc, s33, v157
	v_add_u32_e32 v157, 16, v189
	v_max_i32_e32 v192, v157, v192
	v_cndmask_b32_e32 v70, v183, v70, vcc
	v_add_u32_e32 v195, 43, v194
	v_cmp_gt_i32_e32 vcc, 32, v157
	s_nop 1
	v_cndmask_b32_e32 v157, v193, v195, vcc
	v_cmp_gt_u32_e32 vcc, s33, v192
	v_sub_u32_e32 v192, -11, v189
	v_subrev_u32_e32 v193, 21, v189
	v_cndmask_b32_e32 v87, v183, v87, vcc
	v_cmp_gt_i32_e32 vcc, s33, v157
	v_add_u32_e32 v157, 11, v189
	v_max_i32_e32 v192, v157, v192
	v_cndmask_b32_e32 v71, v183, v71, vcc
	v_add_u32_e32 v195, 48, v194
	v_cmp_gt_i32_e32 vcc, 32, v157
	s_nop 1
	v_cndmask_b32_e32 v157, v193, v195, vcc
	v_cmp_gt_u32_e32 vcc, s33, v192
	v_sub_u32_e32 v192, -10, v189
	v_subrev_u32_e32 v193, 22, v189
	v_cndmask_b32_e32 v88, v183, v88, vcc
	v_cmp_gt_i32_e32 vcc, s33, v157
	v_add_u32_e32 v157, 10, v189
	v_max_i32_e32 v192, v157, v192
	v_cndmask_b32_e32 v72, v183, v72, vcc
	v_add_u32_e32 v195, 49, v194
	v_cmp_gt_i32_e32 vcc, 32, v157
	s_nop 1
	v_cndmask_b32_e32 v157, v193, v195, vcc
	v_cmp_gt_u32_e32 vcc, s33, v192
	v_sub_u32_e32 v192, -9, v189
	v_subrev_u32_e32 v193, 23, v189
	v_cndmask_b32_e32 v89, v183, v89, vcc
	v_cmp_gt_i32_e32 vcc, s33, v157
	v_add_u32_e32 v157, 9, v189
	v_max_i32_e32 v192, v157, v192
	v_cndmask_b32_e32 v73, v183, v73, vcc
	v_add_u32_e32 v195, 50, v194
	v_cmp_gt_i32_e32 vcc, 32, v157
	s_nop 1
	v_cndmask_b32_e32 v157, v193, v195, vcc
	v_cmp_gt_u32_e32 vcc, s33, v192
	v_sub_u32_e32 v192, -8, v189
	v_subrev_u32_e32 v193, 24, v189
	v_cndmask_b32_e32 v90, v183, v90, vcc
	v_cmp_gt_i32_e32 vcc, s33, v157
	v_add_u32_e32 v157, 8, v189
	v_max_i32_e32 v192, v157, v192
	v_cndmask_b32_e32 v74, v183, v74, vcc
	v_add_u32_e32 v195, 51, v194
	v_cmp_gt_i32_e32 vcc, 32, v157
	s_nop 1
	v_cndmask_b32_e32 v157, v193, v195, vcc
	v_cmp_gt_u32_e32 vcc, s33, v192
	v_sub_u32_e32 v192, -3, v189
	v_subrev_u32_e32 v193, 29, v189
	v_cndmask_b32_e32 v91, v183, v91, vcc
	v_cmp_gt_i32_e32 vcc, s33, v157
	v_add_u32_e32 v157, 3, v189
	v_max_i32_e32 v192, v157, v192
	v_cndmask_b32_e32 v75, v183, v75, vcc
	v_add_u32_e32 v195, 56, v194
	v_cmp_gt_i32_e32 vcc, 32, v157
	s_nop 1
	v_cndmask_b32_e32 v157, v193, v195, vcc
	v_cmp_gt_u32_e32 vcc, s33, v192
	v_sub_u32_e32 v192, -2, v189
	v_subrev_u32_e32 v193, 30, v189
	v_cndmask_b32_e32 v92, v183, v92, vcc
	v_cmp_gt_i32_e32 vcc, s33, v157
	v_add_u32_e32 v157, 2, v189
	v_max_i32_e32 v192, v157, v192
	v_cndmask_b32_e32 v76, v183, v76, vcc
	v_add_u32_e32 v195, 57, v194
	v_cmp_gt_i32_e32 vcc, 32, v157
	s_nop 1
	v_cndmask_b32_e32 v157, v193, v195, vcc
	v_cmp_gt_u32_e32 vcc, s33, v192
	v_not_b32_e32 v192, v189
	v_subrev_u32_e32 v193, 31, v189
	v_cndmask_b32_e32 v93, v183, v93, vcc
	v_cmp_gt_i32_e32 vcc, s33, v157
	v_add_u32_e32 v157, 1, v189
	v_max_i32_e32 v192, v157, v192
	v_cndmask_b32_e32 v77, v183, v77, vcc
	v_add_u32_e32 v195, 58, v194
	v_cmp_gt_i32_e32 vcc, 32, v157
	s_nop 1
	v_cndmask_b32_e32 v157, v193, v195, vcc
	v_cmp_gt_u32_e32 vcc, s33, v192
	v_subrev_u32_e32 v192, 32, v189
	v_add_u32_e32 v193, 59, v194
	v_cndmask_b32_e32 v94, v183, v94, vcc
	v_cmp_gt_i32_e32 vcc, s33, v157
	v_sub_u32_e32 v157, 0, v189
	v_max_i32_e32 v157, v189, v157
	v_cndmask_b32_e32 v78, v183, v78, vcc
	v_cmp_gt_i32_e32 vcc, 32, v189
	s_nop 1
	v_cndmask_b32_e32 v192, v192, v193, vcc
	v_cmp_gt_u32_e32 vcc, s33, v157
	s_nop 1
	v_cndmask_b32_e32 v95, v183, v95, vcc
	v_cmp_gt_i32_e32 vcc, s33, v192
	s_nop 1
	v_cndmask_b32_e32 v79, v183, v79, vcc

.LBB0_951:
	v_sub_f32_e32 v64, v64, v157
	v_exp_f32_e32 v193, v64
	v_sub_f32_e32 v64, v81, v157
	v_exp_f32_e32 v194, v64
	v_sub_f32_e32 v64, v65, v157
	v_exp_f32_e32 v195, v64
	v_sub_f32_e32 v64, v82, v157
	v_exp_f32_e32 v196, v64
	v_sub_f32_e32 v64, v66, v157
	v_exp_f32_e32 v197, v64
	v_sub_f32_e32 v64, v83, v157
	v_exp_f32_e32 v198, v64
	v_sub_f32_e32 v64, v67, v157
	v_exp_f32_e32 v199, v64
	v_sub_f32_e32 v64, v84, v157
	v_exp_f32_e32 v84, v64
	v_sub_f32_e32 v64, v68, v157
	v_exp_f32_e32 v200, v64
	v_sub_f32_e32 v64, v85, v157
	v_exp_f32_e32 v85, v64
	v_sub_f32_e32 v64, v69, v157
	v_exp_f32_e32 v201, v64
	v_sub_f32_e32 v64, v86, v157
	v_exp_f32_e32 v86, v64
	v_sub_f32_e32 v64, v70, v157
	v_exp_f32_e32 v202, v64
	v_sub_f32_e32 v64, v87, v157
	v_exp_f32_e32 v87, v64
	v_sub_f32_e32 v64, v71, v157
	v_exp_f32_e32 v203, v64
	v_sub_f32_e32 v64, v88, v157
	v_exp_f32_e32 v88, v64
	v_sub_f32_e32 v64, v72, v157
	v_exp_f32_e32 v204, v64
	v_sub_f32_e32 v64, v89, v157
	v_exp_f32_e32 v89, v64
	v_sub_f32_e32 v64, v73, v157
	v_exp_f32_e32 v205, v64
	v_sub_f32_e32 v64, v90, v157
	v_exp_f32_e32 v90, v64
	v_sub_f32_e32 v64, v74, v157
	v_exp_f32_e32 v206, v64
	v_sub_f32_e32 v64, v91, v157
	v_exp_f32_e32 v91, v64
	v_sub_f32_e32 v64, v75, v157
	v_sub_f32_e32 v80, v80, v157
	v_exp_f32_e32 v207, v64
	v_sub_f32_e32 v64, v92, v157
	v_exp_f32_e32 v192, v80
	v_exp_f32_e32 v92, v64
	v_sub_f32_e32 v64, v76, v157
	v_exp_f32_e32 v208, v64
	v_sub_f32_e32 v64, v93, v157
	v_exp_f32_e32 v93, v64
	v_sub_f32_e32 v64, v77, v157
	v_exp_f32_e32 v209, v64
	v_sub_f32_e32 v64, v94, v157
	v_add_u32_e32 v211, 0x4000, v180
	v_exp_f32_e32 v94, v64
	v_cvt_pk_bf16_f32 v64, v192, v194
	v_cvt_pk_bf16_f32 v65, v196, v198
	v_cvt_pk_bf16_f32 v66, v84, v85
	v_cvt_pk_bf16_f32 v67, v86, v87
	ds_read2_b64 v[68:71], v211 offset0:128 offset1:130
	v_sub_f32_e32 v72, v95, v157
	v_exp_f32_e32 v95, v72
	s_waitcnt lgkmcnt(0)
	s_setprio 1
	v_mfma_f32_32x32x16_bf16 v[32:47], v[64:67], v[68:71], v[32:47]
	s_setprio 0
	v_cvt_pk_bf16_f32 v72, v88, v89
	v_cvt_pk_bf16_f32 v73, v90, v91
	v_cvt_pk_bf16_f32 v74, v92, v93
	v_cvt_pk_bf16_f32 v75, v94, v95
	ds_read2_b64 v[68:71], v211 offset0:132 offset1:134
	v_cvt_pk_bf16_f32 v80, v193, v195
	v_cvt_pk_bf16_f32 v81, v197, v199
	s_waitcnt lgkmcnt(0)
	s_setprio 1
	v_mfma_f32_32x32x16_bf16 v[32:47], v[72:75], v[68:71], v[32:47]
	s_setprio 0
	v_cvt_pk_bf16_f32 v82, v200, v201
	v_cvt_pk_bf16_f32 v83, v202, v203
	ds_read2_b64 v[68:71], v211 offset0:136 offset1:138
	v_sub_f32_e32 v76, v78, v157
	v_exp_f32_e32 v212, v76
	v_sub_f32_e32 v76, v79, v157
	v_exp_f32_e32 v213, v76
	s_waitcnt lgkmcnt(0)
	s_setprio 1
	v_mfma_f32_32x32x16_bf16 v[32:47], v[80:83], v[68:71], v[32:47]
	s_setprio 0
	v_cvt_pk_bf16_f32 v76, v204, v205
	v_cvt_pk_bf16_f32 v77, v206, v207
	v_cvt_pk_bf16_f32 v78, v208, v209
	v_cvt_pk_bf16_f32 v79, v212, v213
	ds_read2_b64 v[68:71], v211 offset0:140 offset1:142
	v_add_u32_e32 v211, 0x5000, v180
	v_add_f32_e32 v192, v192, v193
	s_waitcnt lgkmcnt(0)
	s_setprio 1
	v_mfma_f32_32x32x16_bf16 v[32:47], v[76:79], v[68:71], v[32:47]
	s_setprio 0
	ds_read2_b64 v[68:71], v211 offset0:192 offset1:194
	v_add_f32_e32 v192, 0, v192
	v_add_f32_e32 v193, v194, v195
	v_add_f32_e32 v192, v193, v192
	v_add_f32_e32 v193, v198, v199
	v_add_f32_e32 v84, v84, v200
	v_add_f32_e32 v85, v85, v201
	s_waitcnt lgkmcnt(0)
	s_setprio 1
	v_mfma_f32_32x32x16_bf16 v[48:63], v[64:67], v[68:71], v[48:63]
	s_setprio 0
	ds_read2_b64 v[68:71], v211 offset0:196 offset1:198
	s_add_i32 s43, s43, 64
	s_cmp_eq_u32 s41, s47
	v_subrev_u32_e32 v189, 64, v189
	s_waitcnt lgkmcnt(0)
	s_setprio 1
	v_mfma_f32_32x32x16_bf16 v[48:63], v[72:75], v[68:71], v[48:63]
	ds_read2_b64 v[68:71], v211 offset0:200 offset1:202
	s_waitcnt lgkmcnt(0)
	v_mfma_f32_32x32x16_bf16 v[48:63], v[80:83], v[68:71], v[48:63]
	ds_read2_b64 v[68:71], v211 offset0:204 offset1:206
	v_add_u32_e32 v211, 0x6800, v180
	s_waitcnt lgkmcnt(0)
	v_mfma_f32_32x32x16_bf16 v[48:63], v[76:79], v[68:71], v[48:63]
	ds_read2_b64 v[68:71], v211 offset1:2
	s_waitcnt lgkmcnt(0)
	v_mfma_f32_32x32x16_bf16 v[16:31], v[64:67], v[68:71], v[16:31]
	ds_read2_b64 v[68:71], v211 offset0:4 offset1:6
	s_waitcnt lgkmcnt(0)
	v_mfma_f32_32x32x16_bf16 v[16:31], v[72:75], v[68:71], v[16:31]
	ds_read2_b64 v[68:71], v211 offset0:8 offset1:10
	s_waitcnt lgkmcnt(0)
	v_mfma_f32_32x32x16_bf16 v[16:31], v[80:83], v[68:71], v[16:31]
	s_setprio 0
	v_add_f32_e32 v68, v196, v197
	v_add_f32_e32 v192, v68, v192
	ds_read2_b64 v[68:71], v211 offset0:12 offset1:14
	v_add_f32_e32 v192, v193, v192
	v_add_f32_e32 v84, v84, v192
	v_add_u32_e32 v192, 0x7800, v180
	v_add_f32_e32 v84, v85, v84
	s_waitcnt lgkmcnt(0)
	s_setprio 1
	v_mfma_f32_32x32x16_bf16 v[16:31], v[76:79], v[68:71], v[16:31]
	s_setprio 0
	ds_read2_b64 v[68:71], v192 offset0:64 offset1:66
	v_add_f32_e32 v85, v86, v202
	v_add_f32_e32 v84, v85, v84
	v_add_f32_e32 v85, v87, v203
	s_waitcnt lgkmcnt(0)
	s_setprio 1
	v_mfma_f32_32x32x16_bf16 v[0:15], v[64:67], v[68:71], v[0:15]
	s_setprio 0
	ds_read2_b64 v[64:67], v192 offset0:68 offset1:70
	v_add_f32_e32 v68, v85, v84
	v_add_f32_e32 v69, v88, v204
	v_add_f32_e32 v68, v69, v68
	v_add_f32_e32 v69, v89, v205
	v_add_f32_e32 v68, v69, v68
	v_add_f32_e32 v69, v90, v206
	s_waitcnt lgkmcnt(0)
	s_setprio 1
	v_mfma_f32_32x32x16_bf16 v[0:15], v[72:75], v[64:67], v[0:15]
	s_setprio 0
	ds_read2_b64 v[64:67], v192 offset0:72 offset1:74
	v_add_f32_e32 v68, v69, v68
	v_add_f32_e32 v69, v91, v207
	v_add_f32_e32 v68, v69, v68
	v_add_f32_e32 v69, v92, v208
	v_add_f32_e32 v68, v69, v68
	v_add_f32_e32 v69, v93, v209
	s_waitcnt lgkmcnt(0)
	s_setprio 1
	v_mfma_f32_32x32x16_bf16 v[0:15], v[80:83], v[64:67], v[0:15]
	s_setprio 0
	v_add_f32_e32 v64, v69, v68
	ds_read2_b64 v[66:69], v192 offset0:76 offset1:78
	v_add_f32_e32 v65, v94, v212
	v_add_f32_e32 v64, v65, v64
	v_add_f32_e32 v65, v95, v213
	v_add_f32_e32 v64, v65, v64
	v_fmac_f32_e32 v64, v190, v191
	s_waitcnt lgkmcnt(0)
	s_setprio 1
	v_mfma_f32_32x32x16_bf16 v[0:15], v[76:79], v[66:69], v[0:15]
	s_setprio 0
	s_cbranch_scc1 .LBB0_953
	v_mov_b32_e32 v190, v64
	v_mov_b32_e32 v191, v157
	s_mov_b32 s48, s47
	s_branch .LBB0_936

.LBB0_1057:
	s_add_i32 s41, s41, 1
	s_cmp_lt_i32 s41, s9
	s_mov_b64 s[24:25], s[12:13]
	s_cselect_b64 s[12:13], -1, 0
	s_cmp_eq_u32 s41, s9
	s_mov_b64 s[26:27], s[16:17]
	s_mov_b32 s44, s8
	s_cselect_b64 s[16:17], -1, 0
	s_min_i32 s8, s41, s9
	s_mul_i32 s8, s8, s92
	s_add_i32 s8, s8, s96
	s_min_i32 s8, s8, 0x9f
	s_ashr_i32 s22, s8, 31
	s_lshr_b32 s22, s22, 29
	s_add_i32 s22, s8, s22
	s_ashr_i32 s23, s22, 3
	s_and_b32 s22, s22, -8
	s_and_b64 s[16:17], s[16:17], s[4:5]
	s_sub_i32 s8, s8, s22
	s_cmp_lt_i32 s8, 0
	s_cselect_b32 s22, 21, 20
	s_mul_i32 s8, s8, s22
	s_add_i32 s8, s8, s23
	s_mul_hi_i32 s22, s8, 0x2aaaaaab
	s_lshr_b32 s23, s22, 31
	s_ashr_i32 s22, s22, 1
	s_add_i32 s22, s22, s23
	s_mul_i32 s28, s22, 3
	s_sub_i32 s23, 40, s28
	s_min_u32 s29, s23, 3
	s_mul_i32 s22, s22, 12
	s_sub_i32 s46, s8, s22
	v_cvt_f32_ubyte0_e32 v1, s29
	v_cvt_f32_i32_e32 v0, s46
	v_rcp_iflag_f32_e32 v2, v1
	s_ashr_i32 s8, s46, 30
	s_or_b32 s8, s8, 1
	s_mov_b32 s45, s34
	v_mul_f32_e32 v2, v0, v2
	v_trunc_f32_e32 v2, v2
	v_fma_f32 v0, -v2, v1, v0
	v_cvt_i32_f32_e32 v2, v2
	v_cmp_ge_f32_e64 s[22:23], |v0|, v1
	s_and_b64 s[22:23], s[22:23], exec
	s_cselect_b32 s8, s8, 0
	v_readfirstlane_b32 s22, v2
	s_add_i32 s8, s22, s8
	s_mul_i32 s22, s8, s29
	s_sub_i32 s22, s46, s22
	s_sext_i32_i8 s22, s22
	s_add_i32 s34, s28, s22
	s_or_b64 s[22:23], s[12:13], s[16:17]
	s_lshl_b32 s12, s34, 8
	s_ashr_i32 s13, s12, 31
	s_lshl_b64 s[12:13], s[12:13], 11
	s_add_u32 s12, s6, s12
	s_addc_u32 s13, s7, s13
	s_and_b64 s[16:17], s[22:23], exec
	s_cselect_b32 s46, s13, s25
	s_cselect_b32 s47, s12, s24
	s_bfe_i64 s[16:17], s[8:9], 0x80000
	s_lshl_b64 s[16:17], s[16:17], 19
	s_add_u32 s16, s30, s16
	s_addc_u32 s17, s31, s17
	s_and_b64 s[28:29], s[22:23], exec
	s_cselect_b32 s48, s17, s27
	s_cselect_b32 s49, s16, s26
	s_add_u32 s24, s24, 0x40080
	s_addc_u32 s25, s25, 0
	s_add_u32 s50, s26, 0x100
	v_mov_b32_e32 v0, 0
	s_addc_u32 s51, s27, 0
	s_mov_b32 s56, -2
	v_mov_b32_e32 v1, v0
	v_mov_b32_e32 v2, v0
	v_mov_b32_e32 v3, v0
	v_mov_b32_e32 v4, v0
	v_mov_b32_e32 v5, v0
	v_mov_b32_e32 v6, v0
	v_mov_b32_e32 v7, v0
	v_mov_b32_e32 v16, v0
	v_mov_b32_e32 v17, v0
	v_mov_b32_e32 v18, v0
	v_mov_b32_e32 v19, v0
	v_mov_b32_e32 v20, v0
	v_mov_b32_e32 v21, v0
	v_mov_b32_e32 v22, v0
	v_mov_b32_e32 v23, v0
	v_mov_b32_e32 v32, v0
	v_mov_b32_e32 v33, v0
	v_mov_b32_e32 v34, v0
	v_mov_b32_e32 v35, v0
	v_mov_b32_e32 v36, v0
	v_mov_b32_e32 v37, v0
	v_mov_b32_e32 v38, v0
	v_mov_b32_e32 v39, v0
	v_mov_b32_e32 v48, v0
	v_mov_b32_e32 v49, v0
	v_mov_b32_e32 v50, v0
	v_mov_b32_e32 v51, v0
	v_mov_b32_e32 v52, v0
	v_mov_b32_e32 v53, v0
	v_mov_b32_e32 v54, v0
	v_mov_b32_e32 v55, v0
	v_mov_b32_e32 v8, v0
	v_mov_b32_e32 v9, v0
	v_mov_b32_e32 v10, v0
	v_mov_b32_e32 v11, v0
	v_mov_b32_e32 v12, v0
	v_mov_b32_e32 v13, v0
	v_mov_b32_e32 v14, v0
	v_mov_b32_e32 v15, v0
	v_mov_b32_e32 v24, v0
	v_mov_b32_e32 v25, v0
	v_mov_b32_e32 v26, v0
	v_mov_b32_e32 v27, v0
	v_mov_b32_e32 v28, v0
	v_mov_b32_e32 v29, v0
	v_mov_b32_e32 v30, v0
	v_mov_b32_e32 v31, v0
	v_mov_b32_e32 v40, v0
	v_mov_b32_e32 v41, v0
	v_mov_b32_e32 v42, v0
	v_mov_b32_e32 v43, v0
	v_mov_b32_e32 v44, v0
	v_mov_b32_e32 v45, v0
	v_mov_b32_e32 v46, v0
	v_mov_b32_e32 v47, v0
	v_mov_b32_e32 v56, v0
	v_mov_b32_e32 v57, v0
	v_mov_b32_e32 v58, v0
	v_mov_b32_e32 v59, v0
	v_mov_b32_e32 v60, v0
	v_mov_b32_e32 v61, v0
	v_mov_b32_e32 v62, v0
	v_mov_b32_e32 v63, v0
	v_mov_b32_e32 v64, v0
	v_mov_b32_e32 v65, v0
	v_mov_b32_e32 v66, v0
	v_mov_b32_e32 v67, v0
	v_mov_b32_e32 v68, v0
	v_mov_b32_e32 v69, v0
	v_mov_b32_e32 v70, v0
	v_mov_b32_e32 v71, v0
	v_mov_b32_e32 v80, v0
	v_mov_b32_e32 v81, v0
	v_mov_b32_e32 v82, v0
	v_mov_b32_e32 v83, v0
	v_mov_b32_e32 v84, v0
	v_mov_b32_e32 v85, v0
	v_mov_b32_e32 v86, v0
	v_mov_b32_e32 v87, v0
	v_mov_b32_e32 v96, v0
	s_waitcnt lgkmcnt(0)
	v_mov_b32_e32 v97, v0
	v_mov_b32_e32 v98, v0
	v_mov_b32_e32 v99, v0
	v_mov_b32_e32 v100, v0
	v_mov_b32_e32 v101, v0
	v_mov_b32_e32 v102, v0
	v_mov_b32_e32 v103, v0
	v_mov_b32_e32 v112, v0
	v_mov_b32_e32 v113, v0
	v_mov_b32_e32 v114, v0
	v_mov_b32_e32 v115, v0
	v_mov_b32_e32 v116, v0
	v_mov_b32_e32 v117, v0
	v_mov_b32_e32 v118, v0
	v_mov_b32_e32 v119, v0
	v_mov_b32_e32 v72, v0
	v_mov_b32_e32 v73, v0
	v_mov_b32_e32 v74, v0
	v_mov_b32_e32 v75, v0
	v_mov_b32_e32 v76, v0
	v_mov_b32_e32 v77, v0
	v_mov_b32_e32 v78, v0
	v_mov_b32_e32 v79, v0
	v_mov_b32_e32 v88, v0
	v_mov_b32_e32 v89, v0
	v_mov_b32_e32 v90, v0
	v_mov_b32_e32 v91, v0
	v_mov_b32_e32 v92, v0
	v_mov_b32_e32 v93, v0
	v_mov_b32_e32 v94, v0
	v_mov_b32_e32 v95, v0
	v_mov_b32_e32 v104, v0
	v_mov_b32_e32 v105, v0
	v_mov_b32_e32 v106, v0
	v_mov_b32_e32 v107, v0
	v_mov_b32_e32 v108, v0
	v_mov_b32_e32 v109, v0
	v_mov_b32_e32 v110, v0
	v_mov_b32_e32 v111, v0
	v_mov_b32_e32 v120, v0
	v_mov_b32_e32 v121, v0
	v_mov_b32_e32 v122, v0
	v_mov_b32_e32 v123, v0
	v_mov_b32_e32 v124, v0
	v_mov_b32_e32 v125, v0
	v_mov_b32_e32 v126, v0
	v_mov_b32_e32 v127, v0
	s_nop 0
	s_nop 0
	s_nop 0
	s_nop 0
	s_nop 0
	s_nop 0
	s_nop 0
	s_nop 0
	s_nop 0
	s_nop 0
.LBB0_1058:
	ds_read_b128 v[136:139], v143
	ds_read_b128 v[146:149], v143 offset:1024
	ds_read_b128 v[150:153], v143 offset:2048
	ds_read_b128 v[154:157], v143 offset:3072
	ds_read_b128 v[158:161], v144
	ds_read_b128 v[162:165], v144 offset:1024
	ds_read_b128 v[166:169], v144 offset:2048
	ds_read_b128 v[170:173], v144 offset:3072
	s_add_u32 s26, s24, 0xfffc0080
	s_addc_u32 s27, s25, -1
	s_cmp_eq_u32 s56, 12
	s_cselect_b32 s29, s46, s27
	s_cselect_b32 s28, s47, s26
	s_cselect_b32 s27, s48, s51
	s_cselect_b32 s26, s49, s50
	v_lshl_add_u64 v[206:207], s[24:25], 0, v[132:133]
	s_add_i32 m0, s35, 0xc000
	ds_read_b128 v[174:177], v145
	ds_read_b128 v[178:181], v145 offset:1024
	ds_read_b128 v[182:185], v145 offset:2048
	ds_read_b128 v[186:189], v145 offset:3072
	ds_read_b128 v[190:193], v145 offset:4096
	ds_read_b128 v[194:197], v145 offset:5120
	ds_read_b128 v[198:201], v145 offset:6144
	ds_read_b128 v[202:205], v145 offset:7168
	global_load_lds_dwordx4 v[206:207], off
	v_lshl_add_u64 v[206:207], s[24:25], 0, v[134:135]
	s_add_i32 m0, s35, 0xe000
	s_nop 0
	global_load_lds_dwordx4 v[206:207], off
	s_waitcnt vmcnt(8)
	s_waitcnt lgkmcnt(0)
	s_barrier
	s_setprio 1
	s_waitcnt lgkmcnt(0)
	v_mfma_f32_16x16x32_bf16 v[124:127], v[136:139], v[174:177], v[124:127]
	v_mfma_f32_16x16x32_bf16 v[120:123], v[150:153], v[174:177], v[120:123]
	v_mfma_f32_16x16x32_bf16 v[108:111], v[136:139], v[182:185], v[108:111]
	v_mfma_f32_16x16x32_bf16 v[104:107], v[150:153], v[182:185], v[104:107]
	v_mfma_f32_16x16x32_bf16 v[92:95], v[136:139], v[190:193], v[92:95]
	v_mfma_f32_16x16x32_bf16 v[88:91], v[150:153], v[190:193], v[88:91]
	v_mfma_f32_16x16x32_bf16 v[76:79], v[136:139], v[198:201], v[76:79]
	v_mfma_f32_16x16x32_bf16 v[72:75], v[150:153], v[198:201], v[72:75]
	v_mfma_f32_16x16x32_bf16 v[124:127], v[146:149], v[178:181], v[124:127]
	v_mfma_f32_16x16x32_bf16 v[120:123], v[154:157], v[178:181], v[120:123]
	v_mfma_f32_16x16x32_bf16 v[108:111], v[146:149], v[186:189], v[108:111]
	v_mfma_f32_16x16x32_bf16 v[104:107], v[154:157], v[186:189], v[104:107]
	v_mfma_f32_16x16x32_bf16 v[92:95], v[146:149], v[194:197], v[92:95]
	v_mfma_f32_16x16x32_bf16 v[88:91], v[154:157], v[194:197], v[88:91]
	v_mfma_f32_16x16x32_bf16 v[76:79], v[146:149], v[202:205], v[76:79]
	v_mfma_f32_16x16x32_bf16 v[72:75], v[154:157], v[202:205], v[72:75]
	s_setprio 0
	s_setprio 1
	v_mfma_f32_16x16x32_bf16 v[116:119], v[158:161], v[174:177], v[116:119]
	v_mfma_f32_16x16x32_bf16 v[112:115], v[166:169], v[174:177], v[112:115]
	v_mfma_f32_16x16x32_bf16 v[100:103], v[158:161], v[182:185], v[100:103]
	v_mfma_f32_16x16x32_bf16 v[96:99], v[166:169], v[182:185], v[96:99]
	v_mfma_f32_16x16x32_bf16 v[84:87], v[158:161], v[190:193], v[84:87]
	v_mfma_f32_16x16x32_bf16 v[80:83], v[166:169], v[190:193], v[80:83]
	v_mfma_f32_16x16x32_bf16 v[68:71], v[158:161], v[198:201], v[68:71]
	v_mfma_f32_16x16x32_bf16 v[64:67], v[166:169], v[198:201], v[64:67]
	v_mfma_f32_16x16x32_bf16 v[116:119], v[162:165], v[178:181], v[116:119]
	v_mfma_f32_16x16x32_bf16 v[112:115], v[170:173], v[178:181], v[112:115]
	v_mfma_f32_16x16x32_bf16 v[100:103], v[162:165], v[186:189], v[100:103]
	v_mfma_f32_16x16x32_bf16 v[96:99], v[170:173], v[186:189], v[96:99]
	v_mfma_f32_16x16x32_bf16 v[84:87], v[162:165], v[194:197], v[84:87]
	v_mfma_f32_16x16x32_bf16 v[80:83], v[170:173], v[194:197], v[80:83]
	v_mfma_f32_16x16x32_bf16 v[68:71], v[162:165], v[202:205], v[68:71]
	v_mfma_f32_16x16x32_bf16 v[64:67], v[170:173], v[202:205], v[64:67]
	s_setprio 0
	s_barrier
	s_add_i32 s57, s42, s33
	v_lshl_add_u64 v[206:207], s[26:27], 0, v[130:131]
	s_mov_b32 m0, s57
	ds_read_b128 v[174:177], v145 offset:16384
	ds_read_b128 v[178:181], v145 offset:17408
	ds_read_b128 v[182:185], v145 offset:18432
	ds_read_b128 v[186:189], v145 offset:19456
	ds_read_b128 v[190:193], v145 offset:20480
	ds_read_b128 v[194:197], v145 offset:21504
	ds_read_b128 v[198:201], v145 offset:22528
	ds_read_b128 v[202:205], v145 offset:23552
	global_load_lds_dwordx4 v[206:207], off
	s_add_i32 m0, s57, 0x2000
	s_add_u32 s58, s26, 0x40000
	v_lshl_add_u64 v[208:209], s[26:27], 0, v[128:129]
	s_addc_u32 s59, s27, 0
	s_add_i32 s57, s43, s33
	global_load_lds_dwordx4 v[208:209], off
	v_lshl_add_u64 v[210:211], s[58:59], 0, v[130:131]
	s_mov_b32 m0, s57
	v_lshl_add_u64 v[212:213], s[28:29], 0, v[128:129]
	global_load_lds_dwordx4 v[210:211], off
	v_lshl_add_u64 v[210:211], s[58:59], 0, v[128:129]
	s_add_i32 m0, s57, 0x2000
	s_nop 0
	global_load_lds_dwordx4 v[210:211], off
	v_lshl_add_u64 v[210:211], s[28:29], 0, v[130:131]
	s_mov_b32 m0, s35
	s_nop 0
	global_load_lds_dwordx4 v[210:211], off
	s_mov_b32 m0, s36
	s_nop 0
	global_load_lds_dwordx4 v[212:213], off
	s_waitcnt vmcnt(8)
	s_waitcnt lgkmcnt(0)
	s_barrier
	s_setprio 1
	s_waitcnt lgkmcnt(0)
	v_mfma_f32_16x16x32_bf16 v[60:63], v[136:139], v[174:177], v[60:63]
	v_mfma_f32_16x16x32_bf16 v[56:59], v[150:153], v[174:177], v[56:59]
	v_mfma_f32_16x16x32_bf16 v[44:47], v[136:139], v[182:185], v[44:47]
	v_mfma_f32_16x16x32_bf16 v[40:43], v[150:153], v[182:185], v[40:43]
	v_mfma_f32_16x16x32_bf16 v[28:31], v[136:139], v[190:193], v[28:31]
	v_mfma_f32_16x16x32_bf16 v[24:27], v[150:153], v[190:193], v[24:27]
	v_mfma_f32_16x16x32_bf16 v[12:15], v[136:139], v[198:201], v[12:15]
	v_mfma_f32_16x16x32_bf16 v[8:11], v[150:153], v[198:201], v[8:11]
	v_mfma_f32_16x16x32_bf16 v[60:63], v[146:149], v[178:181], v[60:63]
	v_mfma_f32_16x16x32_bf16 v[56:59], v[154:157], v[178:181], v[56:59]
	v_mfma_f32_16x16x32_bf16 v[44:47], v[146:149], v[186:189], v[44:47]
	v_mfma_f32_16x16x32_bf16 v[40:43], v[154:157], v[186:189], v[40:43]
	v_mfma_f32_16x16x32_bf16 v[28:31], v[146:149], v[194:197], v[28:31]
	v_mfma_f32_16x16x32_bf16 v[24:27], v[154:157], v[194:197], v[24:27]
	v_mfma_f32_16x16x32_bf16 v[12:15], v[146:149], v[202:205], v[12:15]
	v_mfma_f32_16x16x32_bf16 v[8:11], v[154:157], v[202:205], v[8:11]
	s_setprio 0
	s_setprio 1
	v_mfma_f32_16x16x32_bf16 v[52:55], v[158:161], v[174:177], v[52:55]
	v_mfma_f32_16x16x32_bf16 v[48:51], v[166:169], v[174:177], v[48:51]
	v_mfma_f32_16x16x32_bf16 v[36:39], v[158:161], v[182:185], v[36:39]
	v_mfma_f32_16x16x32_bf16 v[32:35], v[166:169], v[182:185], v[32:35]
	v_mfma_f32_16x16x32_bf16 v[20:23], v[158:161], v[190:193], v[20:23]
	v_mfma_f32_16x16x32_bf16 v[16:19], v[166:169], v[190:193], v[16:19]
	v_mfma_f32_16x16x32_bf16 v[4:7], v[158:161], v[198:201], v[4:7]
	v_mfma_f32_16x16x32_bf16 v[0:3], v[166:169], v[198:201], v[0:3]
	v_mfma_f32_16x16x32_bf16 v[52:55], v[162:165], v[178:181], v[52:55]
	v_mfma_f32_16x16x32_bf16 v[48:51], v[170:173], v[178:181], v[48:51]
	v_mfma_f32_16x16x32_bf16 v[36:39], v[162:165], v[186:189], v[36:39]
	v_mfma_f32_16x16x32_bf16 v[32:35], v[170:173], v[186:189], v[32:35]
	v_mfma_f32_16x16x32_bf16 v[20:23], v[162:165], v[194:197], v[20:23]
	v_mfma_f32_16x16x32_bf16 v[16:19], v[170:173], v[194:197], v[16:19]
	v_mfma_f32_16x16x32_bf16 v[4:7], v[162:165], v[202:205], v[4:7]
	v_mfma_f32_16x16x32_bf16 v[0:3], v[170:173], v[202:205], v[0:3]
	s_setprio 0
	s_barrier
	s_add_i32 s57, 0, 0x18000
	s_add_i32 s58, 0, 0x1c000
	v_add_u32_e32 v154, s57, v141
	v_add_u32_e32 v170, s58, v141
	ds_read_b128 v[136:139], v154
	ds_read_b128 v[146:149], v154 offset:1024
	ds_read_b128 v[150:153], v154 offset:2048
	ds_read_b128 v[154:157], v154 offset:3072
	ds_read_b128 v[158:161], v170
	ds_read_b128 v[162:165], v170 offset:1024
	ds_read_b128 v[166:169], v170 offset:2048
	ds_read_b128 v[170:173], v170 offset:3072
	s_add_u32 s28, s28, 0x40000
	s_addc_u32 s29, s29, 0
	s_mov_b32 m0, s37
	v_lshl_add_u64 v[214:215], s[28:29], 0, v[130:131]
	ds_read_b128 v[174:177], v145 offset:32768
	ds_read_b128 v[178:181], v145 offset:33792
	ds_read_b128 v[182:185], v145 offset:34816
	ds_read_b128 v[186:189], v145 offset:35840
	ds_read_b128 v[190:193], v145 offset:36864
	ds_read_b128 v[194:197], v145 offset:37888
	ds_read_b128 v[198:201], v145 offset:38912
	ds_read_b128 v[202:205], v145 offset:39936
	global_load_lds_dwordx4 v[214:215], off
	v_lshl_add_u64 v[214:215], s[28:29], 0, v[128:129]
	s_mov_b32 m0, s38
	s_nop 0
	global_load_lds_dwordx4 v[214:215], off
	s_waitcnt vmcnt(8)
	s_waitcnt lgkmcnt(0)
	s_barrier
	s_setprio 1
	s_waitcnt lgkmcnt(0)
	v_mfma_f32_16x16x32_bf16 v[124:127], v[136:139], v[174:177], v[124:127]
	v_mfma_f32_16x16x32_bf16 v[120:123], v[150:153], v[174:177], v[120:123]
	v_mfma_f32_16x16x32_bf16 v[108:111], v[136:139], v[182:185], v[108:111]
	v_mfma_f32_16x16x32_bf16 v[104:107], v[150:153], v[182:185], v[104:107]
	v_mfma_f32_16x16x32_bf16 v[92:95], v[136:139], v[190:193], v[92:95]
	v_mfma_f32_16x16x32_bf16 v[88:91], v[150:153], v[190:193], v[88:91]
	v_mfma_f32_16x16x32_bf16 v[76:79], v[136:139], v[198:201], v[76:79]
	v_mfma_f32_16x16x32_bf16 v[72:75], v[150:153], v[198:201], v[72:75]
	v_mfma_f32_16x16x32_bf16 v[124:127], v[146:149], v[178:181], v[124:127]
	v_mfma_f32_16x16x32_bf16 v[120:123], v[154:157], v[178:181], v[120:123]
	v_mfma_f32_16x16x32_bf16 v[108:111], v[146:149], v[186:189], v[108:111]
	v_mfma_f32_16x16x32_bf16 v[104:107], v[154:157], v[186:189], v[104:107]
	v_mfma_f32_16x16x32_bf16 v[92:95], v[146:149], v[194:197], v[92:95]
	v_mfma_f32_16x16x32_bf16 v[88:91], v[154:157], v[194:197], v[88:91]
	v_mfma_f32_16x16x32_bf16 v[76:79], v[146:149], v[202:205], v[76:79]
	v_mfma_f32_16x16x32_bf16 v[72:75], v[154:157], v[202:205], v[72:75]
	s_setprio 0
	s_setprio 1
	v_mfma_f32_16x16x32_bf16 v[116:119], v[158:161], v[174:177], v[116:119]
	v_mfma_f32_16x16x32_bf16 v[112:115], v[166:169], v[174:177], v[112:115]
	v_mfma_f32_16x16x32_bf16 v[100:103], v[158:161], v[182:185], v[100:103]
	v_mfma_f32_16x16x32_bf16 v[96:99], v[166:169], v[182:185], v[96:99]
	v_mfma_f32_16x16x32_bf16 v[84:87], v[158:161], v[190:193], v[84:87]
	v_mfma_f32_16x16x32_bf16 v[80:83], v[166:169], v[190:193], v[80:83]
	v_mfma_f32_16x16x32_bf16 v[68:71], v[158:161], v[198:201], v[68:71]
	v_mfma_f32_16x16x32_bf16 v[64:67], v[166:169], v[198:201], v[64:67]
	v_mfma_f32_16x16x32_bf16 v[116:119], v[162:165], v[178:181], v[116:119]
	v_mfma_f32_16x16x32_bf16 v[112:115], v[170:173], v[178:181], v[112:115]
	v_mfma_f32_16x16x32_bf16 v[100:103], v[162:165], v[186:189], v[100:103]
	v_mfma_f32_16x16x32_bf16 v[96:99], v[170:173], v[186:189], v[96:99]
	v_mfma_f32_16x16x32_bf16 v[84:87], v[162:165], v[194:197], v[84:87]
	v_mfma_f32_16x16x32_bf16 v[80:83], v[170:173], v[194:197], v[80:83]
	v_mfma_f32_16x16x32_bf16 v[68:71], v[162:165], v[202:205], v[68:71]
	v_mfma_f32_16x16x32_bf16 v[64:67], v[170:173], v[202:205], v[64:67]
	s_setprio 0
	s_barrier
	s_add_i32 s28, s57, s33
	v_lshl_add_u64 v[206:207], v[206:207], 0, s[18:19]
	s_mov_b32 m0, s28
	ds_read_b128 v[174:177], v145 offset:49152
	ds_read_b128 v[178:181], v145 offset:50176
	ds_read_b128 v[182:185], v145 offset:51200
	ds_read_b128 v[186:189], v145 offset:52224
	ds_read_b128 v[190:193], v145 offset:53248
	ds_read_b128 v[194:197], v145 offset:54272
	ds_read_b128 v[198:201], v145 offset:55296
	ds_read_b128 v[202:205], v145 offset:56320
	global_load_lds_dwordx4 v[206:207], off
	s_add_i32 m0, s28, 0x2000
	s_add_u32 s26, s26, 0x40080
	v_lshl_add_u64 v[206:207], v[208:209], 0, s[18:19]
	s_addc_u32 s27, s27, 0
	s_add_i32 s28, s58, s33
	global_load_lds_dwordx4 v[206:207], off
	v_lshl_add_u64 v[206:207], s[26:27], 0, v[130:131]
	s_mov_b32 m0, s28
	s_nop 0
	global_load_lds_dwordx4 v[206:207], off
	v_lshl_add_u64 v[206:207], s[26:27], 0, v[128:129]
	s_add_i32 m0, s28, 0x2000
	s_nop 0
	global_load_lds_dwordx4 v[206:207], off
	v_lshl_add_u64 v[206:207], v[210:211], 0, s[18:19]
	s_mov_b32 m0, s39
	s_nop 0
	global_load_lds_dwordx4 v[206:207], off
	v_lshl_add_u64 v[206:207], v[212:213], 0, s[18:19]
	s_mov_b32 m0, s40
	s_nop 0
	global_load_lds_dwordx4 v[206:207], off
	s_waitcnt vmcnt(8)
	s_waitcnt lgkmcnt(0)
	s_barrier
	s_setprio 1
	s_waitcnt lgkmcnt(0)
	v_mfma_f32_16x16x32_bf16 v[60:63], v[136:139], v[174:177], v[60:63]
	v_mfma_f32_16x16x32_bf16 v[56:59], v[150:153], v[174:177], v[56:59]
	v_mfma_f32_16x16x32_bf16 v[44:47], v[136:139], v[182:185], v[44:47]
	v_mfma_f32_16x16x32_bf16 v[40:43], v[150:153], v[182:185], v[40:43]
	v_mfma_f32_16x16x32_bf16 v[28:31], v[136:139], v[190:193], v[28:31]
	v_mfma_f32_16x16x32_bf16 v[24:27], v[150:153], v[190:193], v[24:27]
	v_mfma_f32_16x16x32_bf16 v[12:15], v[136:139], v[198:201], v[12:15]
	v_mfma_f32_16x16x32_bf16 v[8:11], v[150:153], v[198:201], v[8:11]
	v_mfma_f32_16x16x32_bf16 v[60:63], v[146:149], v[178:181], v[60:63]
	v_mfma_f32_16x16x32_bf16 v[56:59], v[154:157], v[178:181], v[56:59]
	v_mfma_f32_16x16x32_bf16 v[44:47], v[146:149], v[186:189], v[44:47]
	v_mfma_f32_16x16x32_bf16 v[40:43], v[154:157], v[186:189], v[40:43]
	v_mfma_f32_16x16x32_bf16 v[28:31], v[146:149], v[194:197], v[28:31]
	v_mfma_f32_16x16x32_bf16 v[24:27], v[154:157], v[194:197], v[24:27]
	v_mfma_f32_16x16x32_bf16 v[12:15], v[146:149], v[202:205], v[12:15]
	v_mfma_f32_16x16x32_bf16 v[8:11], v[154:157], v[202:205], v[8:11]
	s_setprio 0
	s_setprio 1
	v_mfma_f32_16x16x32_bf16 v[52:55], v[158:161], v[174:177], v[52:55]
	v_mfma_f32_16x16x32_bf16 v[48:51], v[166:169], v[174:177], v[48:51]
	v_mfma_f32_16x16x32_bf16 v[36:39], v[158:161], v[182:185], v[36:39]
	v_mfma_f32_16x16x32_bf16 v[32:35], v[166:169], v[182:185], v[32:35]
	v_mfma_f32_16x16x32_bf16 v[20:23], v[158:161], v[190:193], v[20:23]
	v_mfma_f32_16x16x32_bf16 v[16:19], v[166:169], v[190:193], v[16:19]
	v_mfma_f32_16x16x32_bf16 v[4:7], v[158:161], v[198:201], v[4:7]
	v_mfma_f32_16x16x32_bf16 v[0:3], v[166:169], v[198:201], v[0:3]
	v_mfma_f32_16x16x32_bf16 v[52:55], v[162:165], v[178:181], v[52:55]
	v_mfma_f32_16x16x32_bf16 v[48:51], v[170:173], v[178:181], v[48:51]
	v_mfma_f32_16x16x32_bf16 v[36:39], v[162:165], v[186:189], v[36:39]
	v_mfma_f32_16x16x32_bf16 v[32:35], v[170:173], v[186:189], v[32:35]
	v_mfma_f32_16x16x32_bf16 v[20:23], v[162:165], v[194:197], v[20:23]
	v_mfma_f32_16x16x32_bf16 v[16:19], v[170:173], v[194:197], v[16:19]
	v_mfma_f32_16x16x32_bf16 v[4:7], v[162:165], v[202:205], v[4:7]
	v_mfma_f32_16x16x32_bf16 v[0:3], v[170:173], v[202:205], v[0:3]
	s_setprio 0
	s_barrier
	s_add_i32 s56, s56, 2
	s_add_u32 s24, s24, 0x100
	s_addc_u32 s25, s25, 0
	s_add_u32 s50, s50, 0x100
	s_addc_u32 s51, s51, 0
	s_cmp_gt_u32 s56, 13
	s_cbranch_scc0 .LBB0_1058
	s_and_b64 vcc, exec, s[20:21]
	s_cbranch_vccz .LBB0_1061
	s_barrier
